# plus: branch-free deferred-rescale decision and v_mov_b64 splat in the sel loop
# baseline (speedup 1.0000x reference)
.LBB0_1513:
	s_cmp_lt_u32 s10, 64
	s_cselect_b64 vcc, -1, 0
	s_sub_i32 s0, s10, 64
	v_lshrrev_b64 v[48:49], s10, v[64:65]
	v_lshrrev_b64 v[50:51], s0, v[66:67]
	v_cndmask_b32_e32 v48, v50, v48, vcc
	s_cmp_eq_u32 s80, s10
	s_cselect_b64 vcc, -1, 0
	v_and_b32_e32 v48, 1, v48
	v_cndmask_b32_e32 v49, 63, v201, vcc
	v_cmp_eq_u32_e32 vcc, 1, v48
	s_nop 1
	v_cndmask_b32_e32 v96, -1, v49, vcc
	v_cmp_lt_i32_e32 vcc, -1, v96
	s_cbranch_vccz .LBB0_1530
	v_lshl_add_u32 v108, v101, 13, v153
	ds_read_b128 v[104:107], v108
	v_cndmask_b32_e64 v32, v227, -v99, vcc
	v_mov_b32_e32 v33, v32
	v_mov_b64_e32 v[34:35], v[32:33]
	v_mov_b64_e32 v[36:37], v[32:33]
	v_mov_b64_e32 v[38:39], v[32:33]
	v_mov_b64_e32 v[40:41], v[32:33]
	v_mov_b64_e32 v[42:43], v[32:33]
	v_mov_b64_e32 v[44:45], v[32:33]
	v_mov_b64_e32 v[46:47], v[32:33]
	v_cmp_gt_u32_e32 vcc, 63, v96
	s_waitcnt lgkmcnt(0)
	v_mfma_f32_32x32x16_bf16 v[48:63], v[104:107], v[68:71], v[32:47]
	ds_read_b128 v[104:107], v108 offset:512
	s_waitcnt lgkmcnt(0)
	v_mfma_f32_32x32x16_bf16 v[32:47], v[104:107], v[68:71], v[32:47]
	ds_read_b128 v[104:107], v108 offset:2048
	s_waitcnt lgkmcnt(0)
	v_mfma_f32_32x32x16_bf16 v[48:63], v[104:107], v[72:75], v[48:63]
	ds_read_b128 v[104:107], v108 offset:2560
	s_waitcnt lgkmcnt(0)
	v_mfma_f32_32x32x16_bf16 v[32:47], v[104:107], v[72:75], v[32:47]
	ds_read_b128 v[104:107], v108 offset:4096
	s_waitcnt lgkmcnt(0)
	v_mfma_f32_32x32x16_bf16 v[48:63], v[104:107], v[76:79], v[48:63]
	ds_read_b128 v[104:107], v108 offset:4608
	s_waitcnt lgkmcnt(0)
	v_mfma_f32_32x32x16_bf16 v[32:47], v[104:107], v[76:79], v[32:47]
	ds_read_b128 v[104:107], v108 offset:6144
	s_waitcnt lgkmcnt(0)
	v_mfma_f32_32x32x16_bf16 v[48:63], v[104:107], v[80:83], v[48:63]
	ds_read_b128 v[104:107], v108 offset:6656
	s_waitcnt lgkmcnt(0)
	v_mfma_f32_32x32x16_bf16 v[32:47], v[104:107], v[80:83], v[32:47]
	s_cbranch_vccz .LBB0_1518
	v_cmp_le_i32_e64 s[0:1], v154, v96
	v_cmp_le_i32_e64 s[2:3], v155, v96
	v_cmp_le_i32_e64 s[4:5], v157, v96
	v_cmp_le_i32_e64 s[14:15], v159, v96
	v_cmp_le_i32_e64 s[16:17], v161, v96
	v_cmp_le_i32_e64 s[18:19], v163, v96
	v_cmp_le_i32_e64 s[20:21], v165, v96
	v_cmp_le_i32_e64 s[22:23], v167, v96
	v_cmp_le_i32_e64 s[24:25], v185, v96
	v_cmp_le_i32_e64 s[26:27], v187, v96
	v_cmp_le_i32_e64 s[28:29], v189, v96
	v_cmp_le_i32_e64 s[30:31], v191, v96
	v_cmp_le_i32_e64 s[34:35], v193, v96
	v_cmp_le_i32_e64 s[36:37], v195, v96
	v_cmp_le_i32_e64 s[38:39], v197, v96
	v_cmp_le_i32_e32 vcc, v114, v96
	v_cndmask_b32_e64 v32, v227, v32, s[0:1]
	v_cmp_lt_i32_e64 s[0:1], v114, v96
	v_cndmask_b32_e64 v33, v227, v33, s[2:3]
	v_cmp_le_i32_e64 s[2:3], v156, v96
	v_cndmask_b32_e64 v34, v227, v34, s[4:5]
	v_cmp_le_i32_e64 s[4:5], v158, v96
	v_cndmask_b32_e64 v35, v227, v35, s[14:15]
	v_cmp_le_i32_e64 s[14:15], v160, v96
	v_cndmask_b32_e64 v36, v227, v36, s[16:17]
	v_cmp_le_i32_e64 s[16:17], v162, v96
	v_cndmask_b32_e64 v37, v227, v37, s[18:19]
	v_cmp_le_i32_e64 s[18:19], v164, v96
	v_cndmask_b32_e64 v38, v227, v38, s[20:21]
	v_cmp_le_i32_e64 s[20:21], v166, v96
	v_cndmask_b32_e64 v39, v227, v39, s[22:23]
	v_cmp_le_i32_e64 s[22:23], v184, v96
	v_cndmask_b32_e64 v40, v227, v40, s[24:25]
	v_cmp_le_i32_e64 s[24:25], v186, v96
	v_cndmask_b32_e64 v41, v227, v41, s[26:27]
	v_cmp_le_i32_e64 s[26:27], v188, v96
	v_cndmask_b32_e64 v42, v227, v42, s[28:29]
	v_cmp_le_i32_e64 s[28:29], v190, v96
	v_cndmask_b32_e64 v43, v227, v43, s[30:31]
	v_cmp_le_i32_e64 s[30:31], v192, v96
	v_cndmask_b32_e64 v44, v227, v44, s[34:35]
	v_cmp_le_i32_e64 s[34:35], v194, v96
	v_cndmask_b32_e64 v45, v227, v45, s[36:37]
	v_cmp_le_i32_e64 s[36:37], v196, v96
	v_cndmask_b32_e64 v46, v227, v46, s[38:39]
	v_cmp_le_i32_e64 s[38:39], v198, v96
	v_cmp_gt_i32_e64 s[40:41], v199, v96
	s_and_saveexec_b64 s[46:47], s[40:41]
	v_mov_b32_e32 v47, s33
	s_or_b64 exec, exec, s[46:47]
	v_cndmask_b32_e64 v49, v227, v49, s[0:1]
	v_cndmask_b32_e32 v48, v227, v48, vcc
	v_cndmask_b32_e64 v50, v227, v50, s[2:3]
	v_cndmask_b32_e64 v51, v227, v51, s[4:5]
	v_cndmask_b32_e64 v52, v227, v52, s[14:15]
	v_cndmask_b32_e64 v53, v227, v53, s[16:17]
	v_cndmask_b32_e64 v54, v227, v54, s[18:19]
	v_cndmask_b32_e64 v55, v227, v55, s[20:21]
	v_cndmask_b32_e64 v56, v227, v56, s[22:23]
	v_cndmask_b32_e64 v57, v227, v57, s[24:25]
	v_cndmask_b32_e64 v58, v227, v58, s[26:27]
	v_cndmask_b32_e64 v59, v227, v59, s[28:29]
	v_cndmask_b32_e64 v60, v227, v60, s[30:31]
	v_cndmask_b32_e64 v61, v227, v61, s[34:35]
	v_cndmask_b32_e64 v62, v227, v62, s[36:37]
	v_cndmask_b32_e64 v63, v227, v63, s[38:39]
.LBB0_1518:
	s_nop 10
	v_max_f32_e32 v96, v32, v32
	v_max_f32_e32 v104, v48, v48
	v_max_f32_e32 v96, v104, v96
	v_max3_f32 v104, v33, v50, v34
	v_max3_f32 v96, v96, v49, v51
	v_max3_f32 v104, v104, v52, v36
	v_max3_f32 v96, v96, v35, v53
	v_max3_f32 v104, v104, v54, v38
	v_max3_f32 v96, v96, v37, v55
	v_max3_f32 v104, v104, v56, v40
	v_max3_f32 v96, v96, v39, v57
	v_max3_f32 v104, v104, v58, v42
	v_max3_f32 v96, v96, v41, v59
	v_max3_f32 v104, v104, v60, v44
	v_max3_f32 v96, v96, v43, v61
	v_max3_f32 v104, v104, v62, v46
	v_max3_f32 v96, v96, v45, v63
	v_max3_f32 v96, v96, v47, v104
	v_mov_b32_e32 v104, v96
	s_nop 1
	v_permlane32_swap_b32_e32 v96, v104
	v_max_f32_e32 v104, v104, v104
	v_max_f32_e32 v96, v96, v96
	v_max_f32_e32 v104, v96, v104
	s_mov_b32 s14, 0x41000000
	v_cmp_lg_f32_e64 s[2:3], s33, v104
	v_cmp_eq_u32_e64 s[0:1], 0, v103
	v_cmp_lt_f32_e64 s[4:5], s14, v104
	s_and_b64 s[0:1], s[0:1], s[2:3]
	s_and_b64 s[4:5], s[4:5], s[2:3]
	s_or_b64 s[4:5], s[4:5], s[0:1]
	v_cndmask_b32_e64 v96, 0, v104, s[4:5]
	v_cndmask_b32_e64 v103, v103, 1, s[2:3]
	v_cmp_neq_f32_e32 vcc, 0, v96
	s_cbranch_vccz .LBB0_1526
	v_exp_f32_e64 v104, -v96
	v_add_f32_e32 v99, v99, v96
	v_pk_add_f32 v[48:49], v[48:49], v[96:97] op_sel_hi:[1,0] neg_lo:[0,1] neg_hi:[0,1]
	v_pk_add_f32 v[32:33], v[32:33], v[96:97] op_sel_hi:[1,0] neg_lo:[0,1] neg_hi:[0,1]
	v_cndmask_b32_e64 v104, v104, 1.0, s[0:1]
	v_mul_f32_e32 v98, v98, v104
	v_pk_add_f32 v[50:51], v[50:51], v[96:97] op_sel_hi:[1,0] neg_lo:[0,1] neg_hi:[0,1]
	v_pk_add_f32 v[34:35], v[34:35], v[96:97] op_sel_hi:[1,0] neg_lo:[0,1] neg_hi:[0,1]
	v_pk_add_f32 v[52:53], v[52:53], v[96:97] op_sel_hi:[1,0] neg_lo:[0,1] neg_hi:[0,1]
	v_pk_add_f32 v[36:37], v[36:37], v[96:97] op_sel_hi:[1,0] neg_lo:[0,1] neg_hi:[0,1]
	v_pk_add_f32 v[54:55], v[54:55], v[96:97] op_sel_hi:[1,0] neg_lo:[0,1] neg_hi:[0,1]
	v_pk_add_f32 v[38:39], v[38:39], v[96:97] op_sel_hi:[1,0] neg_lo:[0,1] neg_hi:[0,1]
	v_pk_add_f32 v[56:57], v[56:57], v[96:97] op_sel_hi:[1,0] neg_lo:[0,1] neg_hi:[0,1]
	v_pk_add_f32 v[40:41], v[40:41], v[96:97] op_sel_hi:[1,0] neg_lo:[0,1] neg_hi:[0,1]
	v_pk_add_f32 v[58:59], v[58:59], v[96:97] op_sel_hi:[1,0] neg_lo:[0,1] neg_hi:[0,1]
	v_pk_add_f32 v[42:43], v[42:43], v[96:97] op_sel_hi:[1,0] neg_lo:[0,1] neg_hi:[0,1]
	v_pk_add_f32 v[60:61], v[60:61], v[96:97] op_sel_hi:[1,0] neg_lo:[0,1] neg_hi:[0,1]
	v_pk_add_f32 v[44:45], v[44:45], v[96:97] op_sel_hi:[1,0] neg_lo:[0,1] neg_hi:[0,1]
	v_pk_add_f32 v[62:63], v[62:63], v[96:97] op_sel_hi:[1,0] neg_lo:[0,1] neg_hi:[0,1]
	v_pk_add_f32 v[46:47], v[46:47], v[96:97] op_sel_hi:[1,0] neg_lo:[0,1] neg_hi:[0,1]
	v_pk_mul_f32 v[30:31], v[30:31], v[104:105] op_sel_hi:[1,0]
	v_pk_mul_f32 v[28:29], v[28:29], v[104:105] op_sel_hi:[1,0]
	v_pk_mul_f32 v[26:27], v[26:27], v[104:105] op_sel_hi:[1,0]
	v_pk_mul_f32 v[24:25], v[24:25], v[104:105] op_sel_hi:[1,0]
	v_pk_mul_f32 v[22:23], v[22:23], v[104:105] op_sel_hi:[1,0]
	v_pk_mul_f32 v[20:21], v[20:21], v[104:105] op_sel_hi:[1,0]
	v_pk_mul_f32 v[18:19], v[18:19], v[104:105] op_sel_hi:[1,0]
	v_pk_mul_f32 v[16:17], v[16:17], v[104:105] op_sel_hi:[1,0]
	v_pk_mul_f32 v[14:15], v[14:15], v[104:105] op_sel_hi:[1,0]
	v_pk_mul_f32 v[12:13], v[12:13], v[104:105] op_sel_hi:[1,0]
	v_pk_mul_f32 v[10:11], v[10:11], v[104:105] op_sel_hi:[1,0]
	v_pk_mul_f32 v[8:9], v[8:9], v[104:105] op_sel_hi:[1,0]
	v_pk_mul_f32 v[6:7], v[6:7], v[104:105] op_sel_hi:[1,0]
	v_pk_mul_f32 v[4:5], v[4:5], v[104:105] op_sel_hi:[1,0]
	v_pk_mul_f32 v[2:3], v[2:3], v[104:105] op_sel_hi:[1,0]
	v_pk_mul_f32 v[0:1], v[0:1], v[104:105] op_sel_hi:[1,0]
